# phase 0 rebalanced: workgroups 144-255 convert layer-0 weights while 0-143 run the modulation GEMV; rest as v34
# speedup vs baseline: 1.0050x; 1.0012x over previous
; #define LAS __attribute__((address_space(3)))
; __device__ void phase_setup(const Params& p, LAS unsigned char* lds) {
;     const int tid = tid_opaque(), wid = tid >> 6, lane = tid & 63;
;     bf16_t* WT = (bf16_t*)(p.ws + WS_WT);
;     LAS float* tl = (LAS float*)lds;
;     for (int l = 0; l < NL; ++l) {
;         bf16_t* W = WT + (size_t)l * W_LAYER;
;         for (int j = 0; j < 2; ++j) {
;             tr_job(tl, p.in[I_FFNIN] + ((size_t)l * 2 + j) * D * (2 * DFF), 2 * DFF, D, 2 * DFF, W + (j ? W_FIN1 : W_FIN0), D, 0, 1);
;             tr_job(tl, p.in[I_FFNOUT] + ((size_t)l * 2 + j) * DFF * D, D, DFF, D, W + (j ? W_FOUT1 : W_FOUT0), DFF, 0, 0);
;         }
;         tr_job(tl, p.in[I_WIN] + (size_t)l * D * PROJ, PROJ, D, PROJ, W + W_WIN, D, 0, 0);
;         tr_job(tl, p.in[I_WBC] + (size_t)l * 256 * D, D, 256, D, W + W_WB, D, 0, 0);
;         tr_job(tl, p.in[I_WBG] + (size_t)l * 256 * D, D, 256, D, W + W_WB, D, 256, 0);
;         tr_job(tl, p.in[I_WBA] + (size_t)l * 512 * D, D, 512, D, W + W_WB, D, 512, 0);
;         tr_job(tl, p.in[I_WOUT] + (size_t)l * D * D, D, D, D, W + W_WO, D, 0, 0);
;         for (int i = bid_opaque() * 512 + tid; i < 65536 / 2; i += gridDim.x * 512) {
;             const float2 v = *(const float2*)(p.in[I_GWS] + (size_t)l * 65536 + 2 * i);
;             *(unsigned*)(W + W_GWS + 2 * i) = cvt_pk_bf16(v.x, v.y);
;         }
;     }
;     { const int gi = bid_opaque() * 512 + tid;
;       if (gi < 1024) { const int pos = gi >> 4, i = gi & 15;
;         const int i4 = i & 3, i16 = i >> 2;
;         float inv = (i4 == 0) ? 1.0f : (i4 == 1) ? 0.5623413251903491f : (i4 == 2) ? 0.31622776601683794f : 0.1778279410038923f;
;         inv *= (i16 == 0) ? 1.0f : (i16 == 1) ? 0.1f : (i16 == 2) ? 0.01f : 0.001f;
;         const float a = (float)pos * inv;
;         const float kq = __builtin_rintf(a * 0.6366197723675814f);
;         float r = __builtin_fmaf(-kq, 1.5707963705062866f, a); r = __builtin_fmaf(kq, 4.371139000186241e-8f, r);
;         const float r2 = r * r;
;         const float sn = r * (1.0f + r2 * (-1.0f / 6 + r2 * (1.0f / 120 + r2 * (-1.0f / 5040 + r2 * (1.0f / 362880)))));
;         const float cs = 1.0f + r2 * (-0.5f + r2 * (1.0f / 24 + r2 * (-1.0f / 720 + r2 * (1.0f / 40320 + r2 * (-1.0f / 3628800)))));
;         const int q = ((int)kq) & 3;
;         const float c = (q == 0) ? cs : (q == 1) ? -sn : (q == 2) ? -cs : sn;
.LBB0_383:
	s_and_b64 vcc, exec, s[0:1]
	s_cbranch_vccz .LBB0_466
	s_waitcnt vmcnt(0)
	s_load_dword s10, s[94:95], 0x0
	s_waitcnt lgkmcnt(0)
	s_max_u32 s10, s10, 1
	s_mov_b32 s15, 24064
	s_mov_b32 s11, s2
	s_mov_b32 s86, 0
	s_cmp_eq_u32 s10, 256
	s_cbranch_scc0 .Lmytr_entry
	s_movk_i32 s15, 6016
	s_mov_b32 s11, 6016
	s_cmp_ge_u32 s2, 144
	s_cbranch_scc0 .Lmytr_entry
	s_sub_u32 s11, s2, 144
	s_movk_i32 s10, 112
